# HID layout [pm][kt][32-col half][256 rows][32 cols]: each FFN-in epilogue store is 1 KB contiguous (8 full lines), FFN-out A loads unchanged in line count
# speedup vs baseline: 1.0059x; 1.0059x over previous
;     __device__ bool next(int i, Unit& u) const { if (!so.next(i >> 1, u)) return false; u.sel = i & 1; return true; }
; #define PG8_STAGE(bufoff, gbase, voff) do { _Pragma("unroll") for (int _i = 0; _i < 2; ++_i) \
;         __builtin_amdgcn_global_load_lds((const unsigned*)((const char*)(gbase) + (voff)[_i]), (PG8_LAS unsigned*)(lds + (bufoff) + ldsw + _i * 8192), 16, 0, 0); } while (0)
; #define PG8_WAIT_V(n) asm volatile("s_waitcnt vmcnt(" #n ")" ::: "memory")
; #define PG8_BAR __builtin_amdgcn_s_barrier()
; template <class Epi, class Sched, bool ALIGN_EPI = false, bool SP2 = false>
; __device__ __forceinline__ void gemm_phase(PG8_LAS unsigned char* lds, const Gemm g, const Sched& S, const Epi& E) {
;     ...
;     const int aoff = lds_byte(wr * 64 + fr, fq * 8), boff = lds_byte(wc * 32 + fr, fq * 8);
;     ...
;     Unit cur, nxt; int ui = 0;
;     if (!S.next(0, cur)) return;
;     f32x4 acc[2][2][4][2];
; #pragma unroll
;     for (int a = 0; a < 2; ++a)
; #pragma unroll
;         for (int b = 0; b < 2; ++b)
; #pragma unroll
;             for (int m = 0; m < 4; ++m)
; #pragma unroll
;                 for (int n = 0; n < 2; ++n) acc[a][b][m][n] = (f32x4){0.f, 0.f, 0.f, 0.f};
;     bf16x8 At[4][2], B0[2][2], B1[2][2];
;     const char* cA = (const char*)(cur.sel ? g.A2 : g.A) + (size_t)cur.pm * tstep; const char* cB = (const char*)(cur.sel ? g.Bt2 : g.Bt) + (size_t)cur.pn * tstep;
;     S.a_ready(cur);
;     if constexpr (SP2) {
;         PG8_STAGE(PG8_SB(0, 0), cB, voffB); PG8_STAGE(PG8_SB(0, 1), cB + hstep, voffB); PG8_STAGE(PG8_SA(0, 0), cA, voffA); PG8_STAGE(PG8_SA(0, 1), cA + hstep, voffA);
;         if (wr == 1) PG8_BAR;
;         PG8_WAIT_V(2); PG8_BAR;
;         PG8_STAGE(PG8_SB(1, 0), cB + kstep, voffB); PG8_STAGE(PG8_SA(1, 0), cA + kstep, voffA); PG8_STAGE(PG8_SB(1, 1), cB + hstep + kstep, voffB);
;         PG8_WAIT_V(6); PG8_BAR;
.LBB0_1010:
	s_mov_b64 s[36:37], 0x80
	s_add_i32 m0, s50, 0x18000
	v_lshl_add_u64 v[8:9], v[8:9], 0, s[36:37]
	s_waitcnt vmcnt(2)
	s_barrier
	global_load_lds_dwordx4 v[8:9], off
	v_lshl_add_u64 v[4:5], v[4:5], 0, s[36:37]
	s_add_i32 m0, s50, 0x1a000
	s_add_i32 s55, s50, 0x8000
	global_load_lds_dwordx4 v[4:5], off
	v_lshl_add_u64 v[4:5], v[6:7], 0, s[36:37]
	s_mov_b32 m0, s55
	s_add_i32 s56, s50, 0xa000
	global_load_lds_dwordx4 v[4:5], off
	v_lshl_add_u64 v[4:5], v[10:11], 0, s[36:37]
	s_mov_b32 m0, s56
	v_lshl_add_u64 v[2:3], v[2:3], 0, s[36:37]
	global_load_lds_dwordx4 v[4:5], off
	s_add_i32 m0, s50, 0x1c000
	v_lshl_add_u64 v[0:1], v[0:1], 0, s[36:37]
	global_load_lds_dwordx4 v[2:3], off
	s_add_i32 m0, s50, 0x1e000
	s_lshr_b32 s1, s1, 26
	global_load_lds_dwordx4 v[0:1], off
	v_lshrrev_b32_e32 v1, 1, v12
	v_and_b32_e32 v1, 24, v1
	v_and_b32_e32 v0, 15, v12
	v_lshlrev_b32_e32 v2, 1, v1
	s_add_i32 s1, s0, s1
	v_lshl_or_b32 v144, s7, 6, v0
	v_lshl_or_b32 v0, v0, 6, v2
	v_lshlrev_b32_e32 v2, 2, v12
	s_ashr_i32 s57, s1, 6
	s_lshl_b32 s1, s7, 13
	v_and_b32_e32 v2, 32, v2
	v_bitop3_b32 v3, v0, s1, v2 bitop3:0xde
	s_lshl_b32 s1, s6, 5
	s_sext_i32_i16 s67, s4
	s_and_b32 s4, s1, 0x60
	s_lshl_b32 s1, s4, 7
	v_bitop3_b32 v145, v0, s1, v2 bitop3:0xde
	v_add_u32_e32 v0, v18, v16
	s_cmp_gt_i32 s0, 63
	v_or_b32_e32 v146, s4, v1
	v_add_lshl_u32 v0, v0, v17, 1
	v_mov_b32_e32 v1, v133
	s_cselect_b64 s[0:1], -1, 0
	s_add_i32 s58, s57, -2
	v_lshl_add_u64 v[136:137], s[10:11], 0, v[0:1]
	v_add_u32_e32 v0, v15, v13
	s_waitcnt vmcnt(6)
	s_cmpk_lt_u32 s5, 0x100
	v_add_lshl_u32 v0, v0, v14, 1
	s_cselect_b64 s[38:39], -1, 0
	v_lshl_add_u64 v[138:139], s[10:11], 0, v[0:1]
	v_cndmask_b32_e64 v0, 0, 1, s[0:1]
	s_add_i32 s61, 0, 0x10000
	s_add_i32 s62, 0, 0x14000
	s_ashr_i32 s59, s30, 31
	s_mov_b32 s60, s30
	v_mov_b64_e32 v[140:141], 0x1600
	v_mov_b64_e32 v[142:143], 0x15ff
	v_add_u32_e32 v147, s61, v145
	v_add_u32_e32 v148, s62, v145
	v_add_u32_e32 v149, 0, v3
	s_movk_i32 s63, 0x40
	v_cmp_ne_u32_e64 s[4:5], 1, v0
	s_barrier
	s_waitcnt vmcnt(0)
	s_branch .LBB0_1013

; __device__ __forceinline__ u32x4 pack8(const f32x4 a, const f32x4 b) { u32x4 w; w.x = cvt_pk_bf16(a[0], a[1]); w.y = cvt_pk_bf16(a[2], a[3]); w.z = cvt_pk_bf16(b[0], b[1]); w.w = cvt_pk_bf16(b[2], b[3]); return w; }
; #define EPI_ROWLOOP _Pragma("unroll") for (int ai = 0; ai < 2; ++ai) _Pragma("unroll") for (int m = 0; m < 4; ++m)
; __device__ __forceinline__ float sigm(float x) { return __builtin_amdgcn_rcpf(1.0f + __builtin_amdgcn_exp2f(x * -1.4426950408889634f)); }
; __device__ __forceinline__ float sigm_new(float x) { return __builtin_amdgcn_rcpf(1.0f + __builtin_amdgcn_exp2f(x * -1.4426950408889634f)); }
; __device__ __forceinline__ f32x4 sigm4_new(const f32x4 v) { f32x4 o; o[0] = sigm_new(v[0]); o[1] = sigm_new(v[1]); o[2] = sigm_new(v[2]); o[3] = sigm_new(v[3]); return o; }
; __device__ __forceinline__ f32x4 silu4_new(const f32x4 v) { return v * sigm4_new(v); }
;     __device__ __forceinline__ void operator()(const f32x4 (&acc)[2][2][4][2], const Unit& u, int wr, int wc, int fr, int fq) const {
;         const int row0 = u.pm * BM + wr * 64 + fr, c0 = u.pn * 128 + wc * 32 + 8 * fq;
;         EPI_ROWLOOP { const int r = row0 + ai * HALF + m * 16;
;             *(u32x4*)(HID + (size_t)r * ldh + c0) = pack8(silu4_new(acc[ai][0][m][0]) * acc[ai][1][m][0], silu4_new(acc[ai][0][m][1]) * acc[ai][1][m][1]); }
.LBB0_1024:
	v_mul_f32_e32 v151, 0xbfb8aa3b, v124
	v_exp_f32_e32 v151, v151
	v_mul_f32_e32 v153, 0xbfb8aa3b, v125
	v_exp_f32_e32 v155, v153
	v_and_b32_e32 v152, 0x60, v146
	v_lshlrev_b32_e32 v152, 8, v152
	v_and_or_b32 v152, v146, 31, v152
	v_add_f32_e32 v151, 1.0, v151
	v_rcp_f32_e32 v154, v151
	v_add_f32_e32 v151, 1.0, v155
	v_mul_f32_e32 v155, 0xbfb8aa3b, v126
	v_exp_f32_e32 v156, v155
	v_mul_f32_e32 v155, 0xbfb8aa3b, v127
	v_exp_f32_e32 v157, v155
	v_rcp_f32_e32 v155, v151
	v_add_f32_e32 v151, 1.0, v156
	v_rcp_f32_e32 v156, v151
	v_add_f32_e32 v151, 1.0, v157
	v_rcp_f32_e32 v157, v151
	v_mul_f32_e32 v151, 0xbfb8aa3b, v116
	v_pk_mul_f32 v[124:125], v[124:125], v[154:155]
	v_exp_f32_e32 v151, v151
	v_mul_f32_e32 v154, 0xbfb8aa3b, v117
	v_exp_f32_e32 v155, v154
	v_pk_mul_f32 v[126:127], v[126:127], v[156:157]
	v_add_f32_e32 v151, 1.0, v151
	v_rcp_f32_e32 v154, v151
	v_add_f32_e32 v151, 1.0, v155
	v_mul_f32_e32 v155, 0xbfb8aa3b, v118
	v_exp_f32_e32 v156, v155
	v_mul_f32_e32 v155, 0xbfb8aa3b, v119
	v_exp_f32_e32 v157, v155
	v_rcp_f32_e32 v155, v151
	v_add_f32_e32 v151, 1.0, v156
	v_rcp_f32_e32 v156, v151
	v_add_f32_e32 v151, 1.0, v157
	v_rcp_f32_e32 v157, v151
	v_pk_mul_f32 v[116:117], v[116:117], v[154:155]
	v_mov_b32_e32 v150, v144
	v_pk_mul_f32 v[112:113], v[112:113], v[116:117]
	v_pk_mul_f32 v[118:119], v[118:119], v[156:157]
	v_ashrrev_i32_e32 v153, 31, v152
	v_pk_mul_f32 v[120:121], v[120:121], v[124:125]
	v_pk_mul_f32 v[114:115], v[114:115], v[118:119]
	v_cvt_pk_bf16_f32 v118, v112, v113
	s_mul_i32 s100, s66, 0x160000
	s_lshl_b32 s101, s67, 16
	s_add_u32 s100, s100, s101
	s_add_u32 s100, s24, s100
	s_addc_u32 s101, s25, 0
	v_mov_b64_e32 v[112:113], s[100:101]
	v_pk_mul_f32 v[122:123], v[122:123], v[126:127]
	v_cvt_pk_bf16_f32 v116, v120, v121
	v_cvt_pk_bf16_f32 v119, v114, v115
	v_mad_i64_i32 v[120:121], s[42:43], v150, s63, v[112:113]
	v_lshlrev_b64 v[114:115], 1, v[152:153]
	v_cvt_pk_bf16_f32 v117, v122, v123
	v_lshl_add_u64 v[120:121], v[120:121], 0, v[114:115]
	global_store_dwordx4 v[120:121], v[116:119], off nt
	v_or_b32_e32 v120, 16, v150
	s_and_b64 vcc, exec, s[6:7]
	v_mul_f32_e32 v116, 0xbfb8aa3b, v108
	v_mul_f32_e32 v117, 0xbfb8aa3b, v109
	v_mul_f32_e32 v118, 0xbfb8aa3b, v110
	v_mul_f32_e32 v119, 0xbfb8aa3b, v111
	v_exp_f32_e32 v116, v116
	v_exp_f32_e32 v117, v117
	v_exp_f32_e32 v118, v118
	v_exp_f32_e32 v119, v119
	v_add_f32_e32 v116, 1.0, v116
	v_add_f32_e32 v117, 1.0, v117
	v_add_f32_e32 v118, 1.0, v118
	v_add_f32_e32 v119, 1.0, v119
	v_rcp_f32_e32 v116, v116
	v_rcp_f32_e32 v117, v117
	v_rcp_f32_e32 v118, v118
	v_rcp_f32_e32 v119, v119
	s_mov_b64 s[6:7], -1
	v_pk_mul_f32 v[108:109], v[108:109], v[116:117]
	v_mul_f32_e32 v116, 0xbfb8aa3b, v100
	v_mul_f32_e32 v117, 0xbfb8aa3b, v101
	v_pk_mul_f32 v[110:111], v[110:111], v[118:119]
	v_mul_f32_e32 v118, 0xbfb8aa3b, v102
	v_mul_f32_e32 v119, 0xbfb8aa3b, v103
	v_exp_f32_e32 v116, v116
	v_exp_f32_e32 v117, v117
	v_exp_f32_e32 v118, v118
	v_exp_f32_e32 v119, v119
	v_add_f32_e32 v116, 1.0, v116
	v_add_f32_e32 v117, 1.0, v117
	v_add_f32_e32 v118, 1.0, v118
	v_add_f32_e32 v119, 1.0, v119
	v_rcp_f32_e32 v116, v116
	v_rcp_f32_e32 v117, v117
	v_rcp_f32_e32 v118, v118
	v_rcp_f32_e32 v119, v119
	v_pk_mul_f32 v[106:107], v[106:107], v[110:111]
	v_pk_mul_f32 v[100:101], v[100:101], v[116:117]
	v_pk_mul_f32 v[104:105], v[104:105], v[108:109]
	v_pk_mul_f32 v[102:103], v[102:103], v[118:119]
	s_nop 0
	v_pk_mul_f32 v[102:103], v[98:99], v[102:103]
	v_pk_mul_f32 v[98:99], v[96:97], v[100:101]
	v_mad_i64_i32 v[100:101], s[42:43], v120, s63, v[112:113]
	v_cvt_pk_bf16_f32 v96, v104, v105
	v_cvt_pk_bf16_f32 v97, v106, v107
	v_cvt_pk_bf16_f32 v98, v98, v99
	v_cvt_pk_bf16_f32 v99, v102, v103
	v_lshl_add_u64 v[100:101], v[100:101], 0, v[114:115]
	global_store_dwordx4 v[100:101], v[96:99], off nt
	v_or_b32_e32 v100, 32, v150
	s_nop 0
	v_mul_f32_e32 v96, 0xbfb8aa3b, v92
	v_mul_f32_e32 v97, 0xbfb8aa3b, v93
	v_mul_f32_e32 v98, 0xbfb8aa3b, v94
	v_mul_f32_e32 v99, 0xbfb8aa3b, v95
	v_exp_f32_e32 v96, v96
	v_exp_f32_e32 v97, v97
	v_exp_f32_e32 v98, v98
	v_exp_f32_e32 v99, v99
	v_add_f32_e32 v96, 1.0, v96
	v_add_f32_e32 v97, 1.0, v97
	v_add_f32_e32 v98, 1.0, v98
	v_add_f32_e32 v99, 1.0, v99
	v_rcp_f32_e32 v96, v96
	v_rcp_f32_e32 v97, v97
	v_rcp_f32_e32 v98, v98
	v_rcp_f32_e32 v99, v99
	v_pk_mul_f32 v[92:93], v[92:93], v[96:97]
	v_mul_f32_e32 v96, 0xbfb8aa3b, v84
	v_mul_f32_e32 v97, 0xbfb8aa3b, v85
	v_pk_mul_f32 v[94:95], v[94:95], v[98:99]
	v_mul_f32_e32 v98, 0xbfb8aa3b, v86
	v_mul_f32_e32 v99, 0xbfb8aa3b, v87
	v_exp_f32_e32 v96, v96
	v_exp_f32_e32 v97, v97
	v_exp_f32_e32 v98, v98
	v_exp_f32_e32 v99, v99
	v_add_f32_e32 v96, 1.0, v96
	v_add_f32_e32 v97, 1.0, v97
	v_add_f32_e32 v98, 1.0, v98
	v_add_f32_e32 v99, 1.0, v99
	v_rcp_f32_e32 v96, v96
	v_rcp_f32_e32 v97, v97
	v_rcp_f32_e32 v98, v98
	v_rcp_f32_e32 v99, v99
	v_pk_mul_f32 v[90:91], v[90:91], v[94:95]
	v_pk_mul_f32 v[84:85], v[84:85], v[96:97]
	v_pk_mul_f32 v[88:89], v[88:89], v[92:93]
	v_pk_mul_f32 v[86:87], v[86:87], v[98:99]
	s_nop 0
	v_pk_mul_f32 v[86:87], v[82:83], v[86:87]
	v_pk_mul_f32 v[82:83], v[80:81], v[84:85]
	v_mad_i64_i32 v[84:85], s[42:43], v100, s63, v[112:113]
	v_cvt_pk_bf16_f32 v80, v88, v89
	v_cvt_pk_bf16_f32 v81, v90, v91
	v_cvt_pk_bf16_f32 v82, v82, v83
	v_cvt_pk_bf16_f32 v83, v86, v87
	v_lshl_add_u64 v[84:85], v[84:85], 0, v[114:115]
	global_store_dwordx4 v[84:85], v[80:83], off nt
	v_or_b32_e32 v84, 48, v150
	s_nop 0
	v_mul_f32_e32 v80, 0xbfb8aa3b, v76
	v_mul_f32_e32 v81, 0xbfb8aa3b, v77
	v_mul_f32_e32 v82, 0xbfb8aa3b, v78
	v_mul_f32_e32 v83, 0xbfb8aa3b, v79
	v_exp_f32_e32 v80, v80
	v_exp_f32_e32 v81, v81
	v_exp_f32_e32 v82, v82
; __device__ __forceinline__ u32x4 pack8(const f32x4 a, const f32x4 b) { u32x4 w; w.x = cvt_pk_bf16(a[0], a[1]); w.y = cvt_pk_bf16(a[2], a[3]); w.z = cvt_pk_bf16(b[0], b[1]); w.w = cvt_pk_bf16(b[2], b[3]); return w; }
; #define EPI_ROWLOOP _Pragma("unroll") for (int ai = 0; ai < 2; ++ai) _Pragma("unroll") for (int m = 0; m < 4; ++m)
; __device__ __forceinline__ float sigm(float x) { return __builtin_amdgcn_rcpf(1.0f + __builtin_amdgcn_exp2f(x * -1.4426950408889634f)); }
; __device__ __forceinline__ float sigm_new(float x) { return __builtin_amdgcn_rcpf(1.0f + __builtin_amdgcn_exp2f(x * -1.4426950408889634f)); }
; __device__ __forceinline__ f32x4 sigm4_new(const f32x4 v) { f32x4 o; o[0] = sigm_new(v[0]); o[1] = sigm_new(v[1]); o[2] = sigm_new(v[2]); o[3] = sigm_new(v[3]); return o; }
; __device__ __forceinline__ f32x4 silu4_new(const f32x4 v) { return v * sigm4_new(v); }
;     __device__ __forceinline__ void operator()(const f32x4 (&acc)[2][2][4][2], const Unit& u, int wr, int wc, int fr, int fq) const {
;         const int row0 = u.pm * BM + wr * 64 + fr, c0 = u.pn * 128 + wc * 32 + 8 * fq;
;         EPI_ROWLOOP { const int r = row0 + ai * HALF + m * 16;
;             *(u32x4*)(HID + (size_t)r * ldh + c0) = pack8(silu4_new(acc[ai][0][m][0]) * acc[ai][1][m][0], silu4_new(acc[ai][0][m][1]) * acc[ai][1][m][1]); }
	v_exp_f32_e32 v83, v83
	v_add_f32_e32 v80, 1.0, v80
	v_add_f32_e32 v81, 1.0, v81
	v_add_f32_e32 v82, 1.0, v82
	v_add_f32_e32 v83, 1.0, v83
	v_rcp_f32_e32 v80, v80
	v_rcp_f32_e32 v81, v81
	v_rcp_f32_e32 v82, v82
	v_rcp_f32_e32 v83, v83
	v_pk_mul_f32 v[76:77], v[76:77], v[80:81]
	v_mul_f32_e32 v80, 0xbfb8aa3b, v68
	v_mul_f32_e32 v81, 0xbfb8aa3b, v69
	v_pk_mul_f32 v[78:79], v[78:79], v[82:83]
	v_mul_f32_e32 v82, 0xbfb8aa3b, v70
	v_mul_f32_e32 v83, 0xbfb8aa3b, v71
	v_exp_f32_e32 v80, v80
	v_exp_f32_e32 v81, v81
	v_exp_f32_e32 v82, v82
	v_exp_f32_e32 v83, v83
	v_add_f32_e32 v80, 1.0, v80
	v_add_f32_e32 v81, 1.0, v81
	v_add_f32_e32 v82, 1.0, v82
	v_add_f32_e32 v83, 1.0, v83
	v_rcp_f32_e32 v80, v80
	v_rcp_f32_e32 v81, v81
	v_rcp_f32_e32 v82, v82
	v_rcp_f32_e32 v83, v83
	v_pk_mul_f32 v[74:75], v[74:75], v[78:79]
	v_pk_mul_f32 v[68:69], v[68:69], v[80:81]
	v_pk_mul_f32 v[72:73], v[72:73], v[76:77]
	v_pk_mul_f32 v[70:71], v[70:71], v[82:83]
	s_nop 0
	v_pk_mul_f32 v[70:71], v[66:67], v[70:71]
	v_pk_mul_f32 v[66:67], v[64:65], v[68:69]
	v_mad_i64_i32 v[68:69], s[42:43], v84, s63, v[112:113]
	v_cvt_pk_bf16_f32 v64, v72, v73
	v_cvt_pk_bf16_f32 v65, v74, v75
	v_cvt_pk_bf16_f32 v66, v66, v67
	v_cvt_pk_bf16_f32 v67, v70, v71
	v_lshl_add_u64 v[68:69], v[68:69], 0, v[114:115]
	global_store_dwordx4 v[68:69], v[64:67], off nt
	v_add_u32_e32 v68, 0x80, v150
	s_nop 0
	v_mul_f32_e32 v64, 0xbfb8aa3b, v60
	v_mul_f32_e32 v65, 0xbfb8aa3b, v61
	v_mul_f32_e32 v66, 0xbfb8aa3b, v62
	v_mul_f32_e32 v67, 0xbfb8aa3b, v63
	v_exp_f32_e32 v64, v64
	v_exp_f32_e32 v65, v65
	v_exp_f32_e32 v66, v66
	v_exp_f32_e32 v67, v67
	v_add_f32_e32 v64, 1.0, v64
	v_add_f32_e32 v65, 1.0, v65
	v_add_f32_e32 v66, 1.0, v66
	v_add_f32_e32 v67, 1.0, v67
	v_rcp_f32_e32 v64, v64
	v_rcp_f32_e32 v65, v65
	v_rcp_f32_e32 v66, v66
	v_rcp_f32_e32 v67, v67
	v_pk_mul_f32 v[60:61], v[60:61], v[64:65]
	v_mul_f32_e32 v64, 0xbfb8aa3b, v52
	v_mul_f32_e32 v65, 0xbfb8aa3b, v53
	v_pk_mul_f32 v[62:63], v[62:63], v[66:67]
	v_mul_f32_e32 v66, 0xbfb8aa3b, v54
	v_mul_f32_e32 v67, 0xbfb8aa3b, v55
	v_exp_f32_e32 v64, v64
	v_exp_f32_e32 v65, v65
	v_exp_f32_e32 v66, v66
	v_exp_f32_e32 v67, v67
	v_add_f32_e32 v64, 1.0, v64
	v_add_f32_e32 v65, 1.0, v65
	v_add_f32_e32 v66, 1.0, v66
	v_add_f32_e32 v67, 1.0, v67
	v_rcp_f32_e32 v64, v64
	v_rcp_f32_e32 v65, v65
	v_rcp_f32_e32 v66, v66
	v_rcp_f32_e32 v67, v67
	v_pk_mul_f32 v[58:59], v[58:59], v[62:63]
	v_pk_mul_f32 v[52:53], v[52:53], v[64:65]
	v_pk_mul_f32 v[56:57], v[56:57], v[60:61]
	v_pk_mul_f32 v[54:55], v[54:55], v[66:67]
	s_nop 0
	v_pk_mul_f32 v[54:55], v[50:51], v[54:55]
	v_pk_mul_f32 v[50:51], v[48:49], v[52:53]
	v_mad_i64_i32 v[52:53], s[42:43], v68, s63, v[112:113]
	v_cvt_pk_bf16_f32 v48, v56, v57
	v_cvt_pk_bf16_f32 v49, v58, v59
	v_cvt_pk_bf16_f32 v50, v50, v51
	v_cvt_pk_bf16_f32 v51, v54, v55
	v_lshl_add_u64 v[52:53], v[52:53], 0, v[114:115]
	global_store_dwordx4 v[52:53], v[48:51], off nt
	v_add_u32_e32 v52, 0x90, v150
	s_nop 0
	v_mul_f32_e32 v48, 0xbfb8aa3b, v44
	v_mul_f32_e32 v49, 0xbfb8aa3b, v45
	v_mul_f32_e32 v50, 0xbfb8aa3b, v46
	v_mul_f32_e32 v51, 0xbfb8aa3b, v47
	v_exp_f32_e32 v48, v48
	v_exp_f32_e32 v49, v49
	v_exp_f32_e32 v50, v50
	v_exp_f32_e32 v51, v51
	v_add_f32_e32 v48, 1.0, v48
	v_add_f32_e32 v49, 1.0, v49
	v_add_f32_e32 v50, 1.0, v50
	v_add_f32_e32 v51, 1.0, v51
	v_rcp_f32_e32 v48, v48
	v_rcp_f32_e32 v49, v49
	v_rcp_f32_e32 v50, v50
	v_rcp_f32_e32 v51, v51
	v_pk_mul_f32 v[44:45], v[44:45], v[48:49]
	v_mul_f32_e32 v48, 0xbfb8aa3b, v36
	v_mul_f32_e32 v49, 0xbfb8aa3b, v37
	v_pk_mul_f32 v[46:47], v[46:47], v[50:51]
	v_mul_f32_e32 v50, 0xbfb8aa3b, v38
	v_mul_f32_e32 v51, 0xbfb8aa3b, v39
	v_exp_f32_e32 v48, v48
	v_exp_f32_e32 v49, v49
	v_exp_f32_e32 v50, v50
	v_exp_f32_e32 v51, v51
	v_add_f32_e32 v48, 1.0, v48
	v_add_f32_e32 v49, 1.0, v49
	v_add_f32_e32 v50, 1.0, v50
	v_add_f32_e32 v51, 1.0, v51
	v_rcp_f32_e32 v48, v48
; __device__ __forceinline__ u32x4 pack8(const f32x4 a, const f32x4 b) { u32x4 w; w.x = cvt_pk_bf16(a[0], a[1]); w.y = cvt_pk_bf16(a[2], a[3]); w.z = cvt_pk_bf16(b[0], b[1]); w.w = cvt_pk_bf16(b[2], b[3]); return w; }
; #define EPI_ROWLOOP _Pragma("unroll") for (int ai = 0; ai < 2; ++ai) _Pragma("unroll") for (int m = 0; m < 4; ++m)
; __device__ __forceinline__ float sigm(float x) { return __builtin_amdgcn_rcpf(1.0f + __builtin_amdgcn_exp2f(x * -1.4426950408889634f)); }
; __device__ __forceinline__ float sigm_new(float x) { return __builtin_amdgcn_rcpf(1.0f + __builtin_amdgcn_exp2f(x * -1.4426950408889634f)); }
; __device__ __forceinline__ f32x4 sigm4_new(const f32x4 v) { f32x4 o; o[0] = sigm_new(v[0]); o[1] = sigm_new(v[1]); o[2] = sigm_new(v[2]); o[3] = sigm_new(v[3]); return o; }
; __device__ __forceinline__ f32x4 silu4_new(const f32x4 v) { return v * sigm4_new(v); }
;     __device__ __forceinline__ void operator()(const f32x4 (&acc)[2][2][4][2], const Unit& u, int wr, int wc, int fr, int fq) const {
;         const int row0 = u.pm * BM + wr * 64 + fr, c0 = u.pn * 128 + wc * 32 + 8 * fq;
;         EPI_ROWLOOP { const int r = row0 + ai * HALF + m * 16;
;             *(u32x4*)(HID + (size_t)r * ldh + c0) = pack8(silu4_new(acc[ai][0][m][0]) * acc[ai][1][m][0], silu4_new(acc[ai][0][m][1]) * acc[ai][1][m][1]); }
	v_rcp_f32_e32 v49, v49
	v_rcp_f32_e32 v50, v50
	v_rcp_f32_e32 v51, v51
	v_pk_mul_f32 v[42:43], v[42:43], v[46:47]
	v_pk_mul_f32 v[36:37], v[36:37], v[48:49]
	v_pk_mul_f32 v[40:41], v[40:41], v[44:45]
	v_pk_mul_f32 v[38:39], v[38:39], v[50:51]
	s_nop 0
	v_pk_mul_f32 v[38:39], v[34:35], v[38:39]
	v_pk_mul_f32 v[34:35], v[32:33], v[36:37]
	v_mad_i64_i32 v[36:37], s[42:43], v52, s63, v[112:113]
	v_cvt_pk_bf16_f32 v32, v40, v41
	v_cvt_pk_bf16_f32 v33, v42, v43
	v_cvt_pk_bf16_f32 v34, v34, v35
	v_cvt_pk_bf16_f32 v35, v38, v39
	v_lshl_add_u64 v[36:37], v[36:37], 0, v[114:115]
	global_store_dwordx4 v[36:37], v[32:35], off nt
	v_add_u32_e32 v36, 0xa0, v150
	s_nop 0
	v_mul_f32_e32 v32, 0xbfb8aa3b, v28
	v_mul_f32_e32 v33, 0xbfb8aa3b, v29
	v_mul_f32_e32 v34, 0xbfb8aa3b, v30
	v_mul_f32_e32 v35, 0xbfb8aa3b, v31
	v_exp_f32_e32 v32, v32
	v_exp_f32_e32 v33, v33
	v_exp_f32_e32 v34, v34
	v_exp_f32_e32 v35, v35
	v_add_f32_e32 v32, 1.0, v32
	v_add_f32_e32 v33, 1.0, v33
	v_add_f32_e32 v34, 1.0, v34
	v_add_f32_e32 v35, 1.0, v35
	v_rcp_f32_e32 v32, v32
	v_rcp_f32_e32 v33, v33
	v_rcp_f32_e32 v34, v34
	v_rcp_f32_e32 v35, v35
	v_pk_mul_f32 v[28:29], v[28:29], v[32:33]
	v_mul_f32_e32 v32, 0xbfb8aa3b, v20
	v_mul_f32_e32 v33, 0xbfb8aa3b, v21
	v_pk_mul_f32 v[30:31], v[30:31], v[34:35]
	v_mul_f32_e32 v34, 0xbfb8aa3b, v22
	v_mul_f32_e32 v35, 0xbfb8aa3b, v23
	v_exp_f32_e32 v32, v32
	v_exp_f32_e32 v33, v33
	v_exp_f32_e32 v34, v34
	v_exp_f32_e32 v35, v35
	v_add_f32_e32 v32, 1.0, v32
	v_add_f32_e32 v33, 1.0, v33
	v_add_f32_e32 v34, 1.0, v34
	v_add_f32_e32 v35, 1.0, v35
	v_rcp_f32_e32 v32, v32
	v_rcp_f32_e32 v33, v33
	v_rcp_f32_e32 v34, v34
	v_rcp_f32_e32 v35, v35
	v_pk_mul_f32 v[26:27], v[26:27], v[30:31]
	v_pk_mul_f32 v[20:21], v[20:21], v[32:33]
	v_pk_mul_f32 v[24:25], v[24:25], v[28:29]
	v_pk_mul_f32 v[22:23], v[22:23], v[34:35]
	s_nop 0
	v_pk_mul_f32 v[22:23], v[18:19], v[22:23]
	v_pk_mul_f32 v[18:19], v[16:17], v[20:21]
	v_mad_i64_i32 v[20:21], s[42:43], v36, s63, v[112:113]
	v_cvt_pk_bf16_f32 v16, v24, v25
	v_cvt_pk_bf16_f32 v17, v26, v27
	v_cvt_pk_bf16_f32 v18, v18, v19
	v_cvt_pk_bf16_f32 v19, v22, v23
	v_lshl_add_u64 v[20:21], v[20:21], 0, v[114:115]
	global_store_dwordx4 v[20:21], v[16:19], off nt
	v_add_u32_e32 v20, 0xb0, v150
	s_nop 0
	v_mul_f32_e32 v16, 0xbfb8aa3b, v12
	v_mul_f32_e32 v17, 0xbfb8aa3b, v13
	v_mul_f32_e32 v18, 0xbfb8aa3b, v14
	v_mul_f32_e32 v19, 0xbfb8aa3b, v15
	v_exp_f32_e32 v16, v16
	v_exp_f32_e32 v17, v17
	v_exp_f32_e32 v18, v18
	v_exp_f32_e32 v19, v19
	v_add_f32_e32 v16, 1.0, v16
	v_add_f32_e32 v17, 1.0, v17
	v_add_f32_e32 v18, 1.0, v18
	v_add_f32_e32 v19, 1.0, v19
	v_rcp_f32_e32 v16, v16
	v_rcp_f32_e32 v17, v17
	v_rcp_f32_e32 v18, v18
	v_rcp_f32_e32 v19, v19
	v_pk_mul_f32 v[12:13], v[12:13], v[16:17]
	v_mul_f32_e32 v16, 0xbfb8aa3b, v4
	v_mul_f32_e32 v17, 0xbfb8aa3b, v5
	v_pk_mul_f32 v[14:15], v[14:15], v[18:19]
	v_mul_f32_e32 v18, 0xbfb8aa3b, v6
	v_mul_f32_e32 v19, 0xbfb8aa3b, v7
	v_exp_f32_e32 v16, v16
	v_exp_f32_e32 v17, v17
	v_exp_f32_e32 v18, v18
	v_exp_f32_e32 v19, v19
	v_add_f32_e32 v16, 1.0, v16
	v_add_f32_e32 v17, 1.0, v17
	v_add_f32_e32 v18, 1.0, v18
	v_add_f32_e32 v19, 1.0, v19
	v_rcp_f32_e32 v16, v16
	v_rcp_f32_e32 v17, v17
	v_rcp_f32_e32 v18, v18
	v_rcp_f32_e32 v19, v19
	v_pk_mul_f32 v[10:11], v[10:11], v[14:15]
	v_pk_mul_f32 v[4:5], v[4:5], v[16:17]
	v_pk_mul_f32 v[8:9], v[8:9], v[12:13]
	v_pk_mul_f32 v[6:7], v[6:7], v[18:19]
	s_nop 0
	v_pk_mul_f32 v[6:7], v[2:3], v[6:7]
	v_pk_mul_f32 v[2:3], v[0:1], v[4:5]
	v_mad_i64_i32 v[4:5], s[42:43], v20, s63, v[112:113]
	v_cvt_pk_bf16_f32 v0, v8, v9
	v_cvt_pk_bf16_f32 v1, v10, v11
	v_cvt_pk_bf16_f32 v2, v2, v3
	v_cvt_pk_bf16_f32 v3, v6, v7
	v_lshl_add_u64 v[4:5], v[4:5], 0, v[114:115]
	global_store_dwordx4 v[4:5], v[0:3], off nt
	s_cbranch_vccnz .LBB0_1012
	s_andn2_b64 vcc, exec, s[14:15]
	s_cbranch_vccnz .LBB0_1011
	s_barrier
	s_branch .LBB0_1011

;     __device__ bool next(int i, Unit& u) const { if (!so.next(i >> 1, u)) return false; u.sel = i & 1; return true; }
; #define PG8_STAGE(bufoff, gbase, voff) do { _Pragma("unroll") for (int _i = 0; _i < 2; ++_i) \
;         __builtin_amdgcn_global_load_lds((const unsigned*)((const char*)(gbase) + (voff)[_i]), (PG8_LAS unsigned*)(lds + (bufoff) + ldsw + _i * 8192), 16, 0, 0); } while (0)
; #define PG8_WAIT_V(n) asm volatile("s_waitcnt vmcnt(" #n ")" ::: "memory")
; #define PG8_BAR __builtin_amdgcn_s_barrier()
; template <class Epi, class Sched, bool ALIGN_EPI = false, bool SP2 = false>
; __device__ __forceinline__ void gemm_phase(PG8_LAS unsigned char* lds, const Gemm g, const Sched& S, const Epi& E) {
;     ...
;     for (int i = 0; i < 2; ++i) { int R, C; stage_rc(tid * 16 + i * 8192, R, C); const int Rb = Epi::PERM ? ((R & ~31) + perm32(R & 31)) : R;
;         voffA[i] = (unsigned)(R * K + C) * 2u; voffB[i] = (unsigned)(Rb * K + C) * 2u; }
;     const size_t kstep = (size_t)(BK * 2);
;     const size_t hstep = (size_t)HALF * K * 2;
;     const size_t tstep = 2 * hstep;
;     const unsigned ldsw = (unsigned)wid * 1024u;
;     const int aoff = lds_byte(wr * 64 + fr, fq * 8), boff = lds_byte(wc * 32 + fr, fq * 8);
;     ...
;     Unit cur, nxt; int ui = 0;
;     if (!S.next(0, cur)) return;
;     f32x4 acc[2][2][4][2];
; #pragma unroll
;     for (int a = 0; a < 2; ++a)
; #pragma unroll
;         for (int b = 0; b < 2; ++b)
; #pragma unroll
;             for (int m = 0; m < 4; ++m)
; #pragma unroll
;                 for (int n = 0; n < 2; ++n) acc[a][b][m][n] = (f32x4){0.f, 0.f, 0.f, 0.f};
;     bf16x8 At[4][2], B0[2][2], B1[2][2];
;     const char* cA = (const char*)(cur.sel ? g.A2 : g.A) + (size_t)cur.pm * tstep; const char* cB = (const char*)(cur.sel ? g.Bt2 : g.Bt) + (size_t)cur.pn * tstep;
;     S.a_ready(cur);
;     if constexpr (SP2) {
;         PG8_STAGE(PG8_SB(0, 0), cB, voffB); PG8_STAGE(PG8_SB(0, 1), cB + hstep, voffB); PG8_STAGE(PG8_SA(0, 0), cA, voffA); PG8_STAGE(PG8_SA(0, 1), cA + hstep, voffA);
;         if (wr == 1) PG8_BAR;
;         PG8_WAIT_V(2); PG8_BAR;
;         PG8_STAGE(PG8_SB(1, 0), cB + kstep, voffB); PG8_STAGE(PG8_SA(1, 0), cA + kstep, voffA); PG8_STAGE(PG8_SB(1, 1), cB + hstep + kstep, voffB);
;         PG8_WAIT_V(6); PG8_BAR;
.LBB0_1086:
	s_add_u32 s10, s28, 0x38900000
	s_addc_u32 s11, s29, 0
	s_and_b64 vcc, exec, s[8:9]
	s_cbranch_vccnz .LBB0_1127
	v_bfe_i32 v2, v12, 27, 1
	v_lshlrev_b32_e32 v0, 4, v12
	v_lshrrev_b32_e32 v2, 22, v2
	v_add_u32_e32 v2, v0, v2
	v_and_b32_e32 v2, 0xfffffc00, v2
	v_sub_u32_e32 v2, v0, v2
	v_ashrrev_i32_e32 v1, 31, v12
	v_lshrrev_b32_e32 v3, 4, v2
	v_lshrrev_b32_e32 v1, 26, v1
	v_bitop3_b32 v2, v3, v2, 32 bitop3:0x6c
	v_add_u32_e32 v1, v12, v1
	v_ashrrev_i32_e32 v4, 31, v2
	v_ashrrev_i32_e32 v1, 6, v1
	v_lshrrev_b32_e32 v4, 26, v4
	v_lshlrev_b32_e32 v3, 3, v1
	v_add_u32_e32 v4, v2, v4
	v_and_b32_e32 v3, -16, v3
	v_ashrrev_i32_e32 v5, 6, v4
	v_lshlrev_b32_e32 v1, 5, v1
	v_add_u32_e32 v3, v5, v3
	v_and_b32_e32 v13, 32, v1
	v_and_b32_e32 v1, 0xc0, v4
	v_sub_u32_e32 v1, v2, v1
	v_mov_b32_e32 v2, 1
	v_lshlrev_b32_e32 v4, 1, v3
	v_lshrrev_b32_e32 v6, 2, v3
	v_and_b32_e32 v5, 3, v5
	s_mov_b32 s1, 0x7fffffe0
	v_ashrrev_i16_sdwa v1, v2, sext(v1) dst_sel:DWORD dst_unused:UNUSED_PAD src0_sel:DWORD src1_sel:BYTE_0
	v_and_b32_e32 v4, 24, v4
	v_and_b32_e32 v6, 4, v6
	v_and_or_b32 v5, v3, s1, v5
	v_bfe_i32 v14, v1, 0, 16
	v_or3_b32 v4, v5, v6, v4
	v_add_u32_e32 v1, v13, v14
	v_lshlrev_b32_e32 v15, 5, v3
	v_lshl_add_u32 v15, v13, 8, v15
	v_mul_lo_u32 v3, v4, s0
	v_add_u32_e32 v0, 0x2000, v0
	v_add_lshl_u32 v128, v14, v15, 1
	v_add_lshl_u32 v130, v3, v1, 1
	v_ashrrev_i32_e32 v1, 31, v0
	v_lshrrev_b32_e32 v1, 22, v1
	v_add_u32_e32 v1, v0, v1
	v_ashrrev_i32_e32 v1, 10, v1
	v_mul_i32_i24_e32 v3, 0x400, v1
	v_sub_u32_e32 v0, v0, v3
	v_lshrrev_b32_e32 v3, 4, v0
	v_bitop3_b32 v0, v3, v0, 32 bitop3:0x6c
	v_ashrrev_i32_e32 v4, 31, v0
	v_lshrrev_b32_e32 v4, 26, v4
	v_lshlrev_b32_e32 v3, 3, v1
	v_add_u32_e32 v4, v0, v4
	v_and_b32_e32 v3, -16, v3
	v_ashrrev_i32_e32 v5, 6, v4
	v_lshlrev_b32_e32 v1, 5, v1
	s_add_u32 s3, s28, 0x1c80000
	v_add_u32_e32 v3, v5, v3
	v_and_b32_e32 v16, 32, v1
	v_and_b32_e32 v1, 0xc0, v4
	v_and_b32_e32 v4, 3, v5
	s_addc_u32 s48, s29, 0
	v_and_or_b32 v4, v3, s1, v4
	s_ashr_i32 s1, s0, 31
	s_lshl_b64 s[12:13], s[0:1], 9
	s_ashr_i32 s7, s67, 31
	s_ashr_i32 s16, s14, 31
	s_mul_i32 s7, s12, s7
	s_mul_hi_u32 s15, s12, s67
	s_lshr_b64 s[34:35], s[0:1], 23
	s_mul_i32 s16, s12, s16
	s_mul_hi_u32 s17, s12, s14
	s_ashr_i32 s4, s6, 6
	s_add_i32 s7, s15, s7
	s_mul_i32 s15, s34, s67
	s_add_i32 s16, s17, s16
	s_mul_i32 s17, s34, s14
	v_sub_u32_e32 v0, v0, v1
	s_ashr_i32 s5, s6, 8
	s_lshl_b64 s[8:9], s[0:1], 8
	s_lshl_b32 s49, s4, 10
	s_add_i32 s7, s7, s15
	s_add_i32 s16, s16, s17
	s_mul_i32 s17, s12, s14
	v_ashrrev_i16_sdwa v0, v2, sext(v0) dst_sel:DWORD dst_unused:UNUSED_PAD src0_sel:DWORD src1_sel:BYTE_0
	v_lshlrev_b32_e32 v1, 1, v3
	v_lshrrev_b32_e32 v2, 2, v3
	s_add_u32 s46, s3, s17
	v_and_b32_e32 v1, 24, v1
	v_and_b32_e32 v2, 4, v2
	s_addc_u32 s47, s48, s16
	s_add_i32 s50, s49, 0
	v_bfe_i32 v17, v0, 0, 16
	v_or3_b32 v1, v4, v2, v1
	s_add_i32 m0, s50, 0x10000
	v_add_u32_e32 v0, v16, v17
	v_mul_lo_u32 v1, v1, s0
	global_load_lds_dwordx4 v130, s[46:47]
	s_add_i32 m0, s50, 0x12000
	v_add_lshl_u32 v134, v1, v0, 1
	s_add_u32 s34, s46, s8
	global_load_lds_dwordx4 v134, s[46:47]
	s_addc_u32 s35, s47, s9
	s_add_i32 m0, s50, 0x14000
	s_mul_i32 s15, s12, s67
	global_load_lds_dwordx4 v130, s[34:35]
	s_add_i32 m0, s50, 0x16000
	s_add_u32 s44, s24, s15
	s_addc_u32 s45, s25, s7
	s_add_i32 s51, s50, 0x2000
	v_lshlrev_b32_e32 v18, 5, v3
	v_lshl_add_u32 v18, v16, 8, v18
	global_load_lds_dwordx4 v134, s[34:35]
	s_mov_b32 m0, s50
	s_add_u32 s36, s44, 0x2000
	v_add_lshl_u32 v132, v17, v18, 1
	global_load_lds_dwordx4 v128, s[44:45]
	s_mov_b32 m0, s51
	s_addc_u32 s37, s45, 0
	s_add_i32 s52, s50, 0x4000
	global_load_lds_dwordx4 v132, s[44:45]
	s_mov_b32 m0, s52
	s_add_i32 s53, s50, 0x6000
	global_load_lds_dwordx4 v128, s[36:37]
	s_mov_b32 m0, s53
	v_mov_b32_e32 v131, 0
	global_load_lds_dwordx4 v132, s[36:37]
	v_mov_b32_e32 v135, v131
	v_mov_b32_e32 v129, v131
	v_mov_b32_e32 v133, v131
	s_cmp_eq_u32 s5, 1
	s_mov_b32 s15, 0
	v_lshl_add_u64 v[8:9], s[46:47], 0, v[130:131]
	v_lshl_add_u64 v[4:5], s[46:47], 0, v[134:135]
	v_lshl_add_u64 v[2:3], s[34:35], 0, v[130:131]
	v_lshl_add_u64 v[0:1], s[34:35], 0, v[134:135]
	v_lshl_add_u64 v[6:7], s[44:45], 0, v[128:129]
	s_cselect_b64 s[34:35], -1, 0
	s_cmp_lg_u32 s5, 1
	v_lshl_add_u64 v[10:11], s[44:45], 0, v[132:133]
	s_cbranch_scc1 .LBB0_1089
	s_barrier
.LBB0_1089:
	s_mov_b64 s[36:37], 0x80
	s_mov_b64 s[100:101], 0x8000
	s_add_i32 m0, s50, 0x18000
	v_lshl_add_u64 v[8:9], v[8:9], 0, s[36:37]
	s_waitcnt vmcnt(2)
	s_barrier
	global_load_lds_dwordx4 v[8:9], off
	v_lshl_add_u64 v[4:5], v[4:5], 0, s[36:37]
	s_add_i32 m0, s50, 0x1a000
	s_add_i32 s54, s50, 0x8000
	global_load_lds_dwordx4 v[4:5], off
	v_lshl_add_u64 v[4:5], v[6:7], 0, s[100:101]
	s_mov_b32 m0, s54
	s_add_i32 s55, s50, 0xa000
	global_load_lds_dwordx4 v[4:5], off
	v_lshl_add_u64 v[4:5], v[10:11], 0, s[100:101]
	s_mov_b32 m0, s55
	v_lshl_add_u64 v[2:3], v[2:3], 0, s[36:37]
	global_load_lds_dwordx4 v[4:5], off
	s_add_i32 m0, s50, 0x1c000
	v_lshl_add_u64 v[0:1], v[0:1], 0, s[36:37]
	global_load_lds_dwordx4 v[2:3], off
	s_add_i32 m0, s50, 0x1e000
	s_lshr_b32 s1, s1, 26
	global_load_lds_dwordx4 v[0:1], off
	v_bfe_u32 v1, v12, 4, 2
	v_and_b32_e32 v0, 15, v12
	v_lshlrev_b32_e32 v3, 4, v1
	s_add_i32 s1, s0, s1
	v_lshl_or_b32 v148, s5, 6, v0
	v_lshl_or_b32 v0, v0, 6, v3
	v_lshlrev_b32_e32 v3, 2, v12
	s_and_b32 s56, s4, 3
	s_ashr_i32 s57, s1, 6
	s_lshl_b32 s1, s5, 13
	v_and_b32_e32 v3, 32, v3
	v_bitop3_b32 v4, v0, s1, v3 bitop3:0xde
	s_lshl_b32 s1, s56, 12
	s_cmp_gt_i32 s0, 63
	v_bitop3_b32 v149, v0, s1, v3 bitop3:0xde
	s_cselect_b64 s[38:39], -1, 0
	s_add_i32 s58, s57, -2
	v_mov_b32_e32 v0, v15
	v_lshlrev_b32_e32 v2, 3, v1
	s_cmpk_lt_u32 s6, 0x100
	v_cmp_eq_u32_e64 s[6:7], 0, v1
	v_add_lshl_u32 v0, v0, v14, 1
	v_mov_b32_e32 v1, v131
	s_waitcnt vmcnt(6)
	s_mov_b64 s[98:99], 0x2000
	v_lshl_add_u64 v[136:137], s[98:99], 0, v[0:1]
	v_mov_b32_e32 v0, v18
	s_cselect_b64 s[40:41], -1, 0
	v_add_lshl_u32 v0, v0, v17, 1
	s_add_i32 s62, 0, 0x10000
	s_add_i32 s63, 0, 0x14000
	v_lshl_or_b32 v150, s56, 5, v2
	s_ashr_i32 s59, s30, 31
	s_mov_b32 s60, s30
	s_ashr_i32 s61, s2, 31
	s_mov_b64 s[98:99], 0x2000
	v_lshl_add_u64 v[138:139], s[98:99], 0, v[0:1]
	v_mov_b64_e32 v[140:141], 0x400
	v_mov_b64_e32 v[142:143], 0x3ff
	v_add_u32_e32 v151, s62, v149
	v_add_u32_e32 v152, s63, v149
	v_add_u32_e32 v153, 0, v4
	v_mbcnt_hi_u32_b32 v154, -1, v234
	s_mov_b32 s64, 0
	s_barrier
	s_branch .LBB0_1092

; #define PG8_STAGE(bufoff, gbase, voff) do { _Pragma("unroll") for (int _i = 0; _i < 2; ++_i) \
;         __builtin_amdgcn_global_load_lds((const unsigned*)((const char*)(gbase) + (voff)[_i]), (PG8_LAS unsigned*)(lds + (bufoff) + ldsw + _i * 8192), 16, 0, 0); } while (0)
; #define PG8_LDA(dst, b, h) do { _Pragma("unroll") for (int m = 0; m < 4; ++m) _Pragma("unroll") for (int k = 0; k < 2; ++k) dst[m][k] = *(const PG8_LAS bf16x8*)(lds + PG8_SA(b, h) + aoff + m * 2048 + k * 1024); } while (0)
; #define PG8_LDB(dst, b, h) do { _Pragma("unroll") for (int n = 0; n < 2; ++n) _Pragma("unroll") for (int k = 0; k < 2; ++k) dst[n][k] = *(const PG8_LAS bf16x8*)(lds + PG8_SB(b, h) + boff + n * 2048 + k * 1024); } while (0)
; #define PG8_MMA(ai, bj, At, Bt) do { __builtin_amdgcn_s_setprio(1); _Pragma("unroll") for (int m = 0; m < 4; ++m) _Pragma("unroll") for (int n = 0; n < 2; ++n) _Pragma("unroll") for (int k = 0; k < 2; ++k) \
;         acc[ai][bj][m][n] = __builtin_amdgcn_mfma_f32_16x16x32_bf16(Bt[n][k], At[m][k], acc[ai][bj][m][n], 0, 0, 0); __builtin_amdgcn_s_setprio(0); } while (0)
; #define PG8_WAIT_V(n) asm volatile("s_waitcnt vmcnt(" #n ")" ::: "memory")
; #define PG8_WAIT_L(n) asm volatile("s_waitcnt lgkmcnt(" #n ")" ::: "memory")
; #define PG8_BAR __builtin_amdgcn_s_barrier()
; #define PG8_SCHED __builtin_amdgcn_sched_barrier(0)
; template <class Epi, class Sched, bool ALIGN_EPI = false, bool SP2 = false>
; __device__ __forceinline__ void gemm_phase(PG8_LAS unsigned char* lds, const Gemm g, const Sched& S, const Epi& E) {
;     ...
;             PG8_LDB(B0, 0, 0); PG8_LDB(B1, 0, 1); PG8_SCHED; PG8_LDA(At, 0, 0); PG8_STAGE(PG8_SA(1, 1), a1 + hstep, voffA);
;             PG8_WAIT_V(8); PG8_WAIT_L(0); PG8_BAR; PG8_MMA(0, 0, At, B0); PG8_MMA(0, 1, At, B1); PG8_BAR; PG8_SCHED;
;             PG8_LDA(At, 0, 1); PG8_STAGE(PG8_SB(0, 0), b2, voffB); PG8_STAGE(PG8_SB(0, 1), b2 + hstep, voffB); PG8_STAGE(PG8_SA(0, 0), a2, voffA);
;             PG8_WAIT_V(8); PG8_WAIT_L(0); PG8_BAR; PG8_MMA(1, 0, At, B0); PG8_MMA(1, 1, At, B1); PG8_BAR; PG8_SCHED;
.LBB0_1104:
	ds_read_b128 v[144:147], v151
	ds_read_b128 v[156:159], v151 offset:1024
	ds_read_b128 v[160:163], v151 offset:2048
	ds_read_b128 v[164:167], v151 offset:3072
	ds_read_b128 v[168:171], v152
	ds_read_b128 v[172:175], v152 offset:1024
	ds_read_b128 v[176:179], v152 offset:2048
	ds_read_b128 v[180:183], v152 offset:3072
	s_add_i32 s70, s46, 2
	s_add_u32 s16, s44, 0x8000
	s_addc_u32 s17, s45, 0
	s_cmp_eq_u32 s58, s46
	s_cselect_b32 s46, s0, s16
	s_cselect_b32 s47, s1, s17
	s_cselect_b32 s73, s43, s69
	s_cselect_b32 s72, s42, s68
	v_lshl_add_u64 v[218:219], s[44:45], 0, v[136:137]
	s_add_i32 m0, s50, 0xc000
	ds_read_b128 v[184:187], v153
	ds_read_b128 v[188:191], v153 offset:1024
	ds_read_b128 v[192:195], v153 offset:2048
	ds_read_b128 v[196:199], v153 offset:3072
	ds_read_b128 v[202:205], v153 offset:4096
	ds_read_b128 v[206:209], v153 offset:5120
	ds_read_b128 v[210:213], v153 offset:6144
	ds_read_b128 v[214:217], v153 offset:7168
	global_load_lds_dwordx4 v[218:219], off
	v_lshl_add_u64 v[218:219], s[44:45], 0, v[138:139]
	s_add_i32 m0, s50, 0xe000
	s_nop 0
	global_load_lds_dwordx4 v[218:219], off
	s_waitcnt vmcnt(8)
	s_waitcnt lgkmcnt(0)
	s_barrier
	s_setprio 1
	s_waitcnt lgkmcnt(0)
	v_mfma_f32_16x16x32_bf16 v[124:127], v[144:147], v[184:187], v[124:127]
	v_mfma_f32_16x16x32_bf16 v[120:123], v[160:163], v[184:187], v[120:123]
	v_mfma_f32_16x16x32_bf16 v[108:111], v[144:147], v[192:195], v[108:111]
	v_mfma_f32_16x16x32_bf16 v[104:107], v[160:163], v[192:195], v[104:107]
	v_mfma_f32_16x16x32_bf16 v[92:95], v[144:147], v[202:205], v[92:95]
	v_mfma_f32_16x16x32_bf16 v[88:91], v[160:163], v[202:205], v[88:91]
	v_mfma_f32_16x16x32_bf16 v[76:79], v[144:147], v[210:213], v[76:79]
	v_mfma_f32_16x16x32_bf16 v[72:75], v[160:163], v[210:213], v[72:75]
	v_mfma_f32_16x16x32_bf16 v[124:127], v[156:159], v[188:191], v[124:127]
	v_mfma_f32_16x16x32_bf16 v[120:123], v[164:167], v[188:191], v[120:123]
	v_mfma_f32_16x16x32_bf16 v[108:111], v[156:159], v[196:199], v[108:111]
	v_mfma_f32_16x16x32_bf16 v[104:107], v[164:167], v[196:199], v[104:107]
	v_mfma_f32_16x16x32_bf16 v[92:95], v[156:159], v[206:209], v[92:95]
	v_mfma_f32_16x16x32_bf16 v[88:91], v[164:167], v[206:209], v[88:91]
	v_mfma_f32_16x16x32_bf16 v[76:79], v[156:159], v[214:217], v[76:79]
	v_mfma_f32_16x16x32_bf16 v[72:75], v[164:167], v[214:217], v[72:75]
	s_setprio 0
	s_setprio 1
	v_mfma_f32_16x16x32_bf16 v[116:119], v[168:171], v[184:187], v[116:119]
	v_mfma_f32_16x16x32_bf16 v[112:115], v[176:179], v[184:187], v[112:115]
	v_mfma_f32_16x16x32_bf16 v[100:103], v[168:171], v[192:195], v[100:103]
	v_mfma_f32_16x16x32_bf16 v[96:99], v[176:179], v[192:195], v[96:99]
	v_mfma_f32_16x16x32_bf16 v[84:87], v[168:171], v[202:205], v[84:87]
	v_mfma_f32_16x16x32_bf16 v[80:83], v[176:179], v[202:205], v[80:83]
	v_mfma_f32_16x16x32_bf16 v[68:71], v[168:171], v[210:213], v[68:71]
	v_mfma_f32_16x16x32_bf16 v[64:67], v[176:179], v[210:213], v[64:67]
	v_mfma_f32_16x16x32_bf16 v[116:119], v[172:175], v[188:191], v[116:119]
	v_mfma_f32_16x16x32_bf16 v[112:115], v[180:183], v[188:191], v[112:115]
	v_mfma_f32_16x16x32_bf16 v[100:103], v[172:175], v[196:199], v[100:103]
	v_mfma_f32_16x16x32_bf16 v[96:99], v[180:183], v[196:199], v[96:99]
	v_mfma_f32_16x16x32_bf16 v[84:87], v[172:175], v[206:209], v[84:87]
	v_mfma_f32_16x16x32_bf16 v[80:83], v[180:183], v[206:209], v[80:83]
	v_mfma_f32_16x16x32_bf16 v[68:71], v[172:175], v[214:217], v[68:71]
	v_mfma_f32_16x16x32_bf16 v[64:67], v[180:183], v[214:217], v[64:67]
	s_setprio 0
	s_barrier
	s_add_i32 s16, s62, s49
	v_lshl_add_u64 v[218:219], s[72:73], 0, v[130:131]
	s_mov_b32 m0, s16
	ds_read_b128 v[184:187], v153 offset:16384
	ds_read_b128 v[188:191], v153 offset:17408
	ds_read_b128 v[192:195], v153 offset:18432
	ds_read_b128 v[196:199], v153 offset:19456
	ds_read_b128 v[202:205], v153 offset:20480
	ds_read_b128 v[206:209], v153 offset:21504
	ds_read_b128 v[210:213], v153 offset:22528
	ds_read_b128 v[214:217], v153 offset:23552
	global_load_lds_dwordx4 v[218:219], off
	s_add_i32 m0, s16, 0x2000
	v_lshl_add_u64 v[220:221], s[72:73], 0, v[134:135]
	s_add_u32 s72, s72, s8
	s_addc_u32 s73, s73, s9
	s_add_i32 s16, s63, s49
	global_load_lds_dwordx4 v[220:221], off
	v_lshl_add_u64 v[222:223], s[72:73], 0, v[130:131]
	s_mov_b32 m0, s16
	v_lshl_add_u64 v[224:225], s[72:73], 0, v[134:135]
	global_load_lds_dwordx4 v[222:223], off
	s_add_i32 m0, s16, 0x2000
	v_lshl_add_u64 v[226:227], s[46:47], 0, v[128:129]
	global_load_lds_dwordx4 v[224:225], off
	s_mov_b32 m0, s50
	v_lshl_add_u64 v[228:229], s[46:47], 0, v[132:133]
	global_load_lds_dwordx4 v[226:227], off
	s_mov_b32 m0, s51
	s_nop 0
	global_load_lds_dwordx4 v[228:229], off
	s_waitcnt vmcnt(8)
	s_waitcnt lgkmcnt(0)
	s_barrier
; #define PG8_STAGE(bufoff, gbase, voff) do { _Pragma("unroll") for (int _i = 0; _i < 2; ++_i) \
;         __builtin_amdgcn_global_load_lds((const unsigned*)((const char*)(gbase) + (voff)[_i]), (PG8_LAS unsigned*)(lds + (bufoff) + ldsw + _i * 8192), 16, 0, 0); } while (0)
; #define PG8_LDA(dst, b, h) do { _Pragma("unroll") for (int m = 0; m < 4; ++m) _Pragma("unroll") for (int k = 0; k < 2; ++k) dst[m][k] = *(const PG8_LAS bf16x8*)(lds + PG8_SA(b, h) + aoff + m * 2048 + k * 1024); } while (0)
; #define PG8_LDB(dst, b, h) do { _Pragma("unroll") for (int n = 0; n < 2; ++n) _Pragma("unroll") for (int k = 0; k < 2; ++k) dst[n][k] = *(const PG8_LAS bf16x8*)(lds + PG8_SB(b, h) + boff + n * 2048 + k * 1024); } while (0)
; #define PG8_MMA(ai, bj, At, Bt) do { __builtin_amdgcn_s_setprio(1); _Pragma("unroll") for (int m = 0; m < 4; ++m) _Pragma("unroll") for (int n = 0; n < 2; ++n) _Pragma("unroll") for (int k = 0; k < 2; ++k) \
;         acc[ai][bj][m][n] = __builtin_amdgcn_mfma_f32_16x16x32_bf16(Bt[n][k], At[m][k], acc[ai][bj][m][n], 0, 0, 0); __builtin_amdgcn_s_setprio(0); } while (0)
; #define PG8_WAIT_V(n) asm volatile("s_waitcnt vmcnt(" #n ")" ::: "memory")
; #define PG8_WAIT_L(n) asm volatile("s_waitcnt lgkmcnt(" #n ")" ::: "memory")
; #define PG8_BAR __builtin_amdgcn_s_barrier()
; #define PG8_SCHED __builtin_amdgcn_sched_barrier(0)
; template <class Epi, class Sched, bool ALIGN_EPI = false, bool SP2 = false>
; __device__ __forceinline__ void gemm_phase(PG8_LAS unsigned char* lds, const Gemm g, const Sched& S, const Epi& E) {
;     ...
;             PG8_WAIT_V(8); PG8_WAIT_L(0); PG8_BAR; PG8_MMA(1, 0, At, B0); PG8_MMA(1, 1, At, B1); PG8_BAR; PG8_SCHED;
;             PG8_LDB(B0, 1, 0); PG8_LDB(B1, 1, 1); PG8_SCHED; PG8_LDA(At, 1, 0); PG8_STAGE(PG8_SA(0, 1), a2 + hstep, voffA);
;             PG8_WAIT_V(8); PG8_WAIT_L(0); PG8_BAR; PG8_MMA(0, 0, At, B0); PG8_MMA(0, 1, At, B1); PG8_BAR; PG8_SCHED;
;             PG8_LDA(At, 1, 1); PG8_STAGE(PG8_SB(1, 0), b3, voffB); PG8_STAGE(PG8_SB(1, 1), b3 + hstep, voffB); PG8_STAGE(PG8_SA(1, 0), a3, voffA);
	s_setprio 1
	s_waitcnt lgkmcnt(0)
	v_mfma_f32_16x16x32_bf16 v[60:63], v[144:147], v[184:187], v[60:63]
	v_mfma_f32_16x16x32_bf16 v[56:59], v[160:163], v[184:187], v[56:59]
	v_mfma_f32_16x16x32_bf16 v[44:47], v[144:147], v[192:195], v[44:47]
	v_mfma_f32_16x16x32_bf16 v[40:43], v[160:163], v[192:195], v[40:43]
	v_mfma_f32_16x16x32_bf16 v[28:31], v[144:147], v[202:205], v[28:31]
	v_mfma_f32_16x16x32_bf16 v[24:27], v[160:163], v[202:205], v[24:27]
	v_mfma_f32_16x16x32_bf16 v[12:15], v[144:147], v[210:213], v[12:15]
	v_mfma_f32_16x16x32_bf16 v[8:11], v[160:163], v[210:213], v[8:11]
	v_mfma_f32_16x16x32_bf16 v[60:63], v[156:159], v[188:191], v[60:63]
	v_mfma_f32_16x16x32_bf16 v[56:59], v[164:167], v[188:191], v[56:59]
	v_mfma_f32_16x16x32_bf16 v[44:47], v[156:159], v[196:199], v[44:47]
	v_mfma_f32_16x16x32_bf16 v[40:43], v[164:167], v[196:199], v[40:43]
	v_mfma_f32_16x16x32_bf16 v[28:31], v[156:159], v[206:209], v[28:31]
	v_mfma_f32_16x16x32_bf16 v[24:27], v[164:167], v[206:209], v[24:27]
	v_mfma_f32_16x16x32_bf16 v[12:15], v[156:159], v[214:217], v[12:15]
	v_mfma_f32_16x16x32_bf16 v[8:11], v[164:167], v[214:217], v[8:11]
	s_setprio 0
	s_setprio 1
	v_mfma_f32_16x16x32_bf16 v[52:55], v[168:171], v[184:187], v[52:55]
	v_mfma_f32_16x16x32_bf16 v[48:51], v[176:179], v[184:187], v[48:51]
	v_mfma_f32_16x16x32_bf16 v[36:39], v[168:171], v[192:195], v[36:39]
	v_mfma_f32_16x16x32_bf16 v[32:35], v[176:179], v[192:195], v[32:35]
	v_mfma_f32_16x16x32_bf16 v[20:23], v[168:171], v[202:205], v[20:23]
	v_mfma_f32_16x16x32_bf16 v[16:19], v[176:179], v[202:205], v[16:19]
	v_mfma_f32_16x16x32_bf16 v[4:7], v[168:171], v[210:213], v[4:7]
	v_mfma_f32_16x16x32_bf16 v[0:3], v[176:179], v[210:213], v[0:3]
	v_mfma_f32_16x16x32_bf16 v[52:55], v[172:175], v[188:191], v[52:55]
	v_mfma_f32_16x16x32_bf16 v[48:51], v[180:183], v[188:191], v[48:51]
	v_mfma_f32_16x16x32_bf16 v[36:39], v[172:175], v[196:199], v[36:39]
	v_mfma_f32_16x16x32_bf16 v[32:35], v[180:183], v[196:199], v[32:35]
	v_mfma_f32_16x16x32_bf16 v[20:23], v[172:175], v[206:209], v[20:23]
	v_mfma_f32_16x16x32_bf16 v[16:19], v[180:183], v[206:209], v[16:19]
	v_mfma_f32_16x16x32_bf16 v[4:7], v[172:175], v[214:217], v[4:7]
	v_mfma_f32_16x16x32_bf16 v[0:3], v[180:183], v[214:217], v[0:3]
	s_setprio 0
	s_barrier
	s_add_i32 s16, 0, 0x18000
	v_add_u32_e32 v155, s16, v149
	s_add_i32 s17, 0, 0x1c000
	ds_read_b128 v[144:147], v155
	ds_read_b128 v[156:159], v155 offset:1024
	ds_read_b128 v[160:163], v155 offset:2048
	ds_read_b128 v[164:167], v155 offset:3072
	v_add_u32_e32 v155, s17, v149
	ds_read_b128 v[168:171], v155
	ds_read_b128 v[172:175], v155 offset:1024
	ds_read_b128 v[176:179], v155 offset:2048
	ds_read_b128 v[180:183], v155 offset:3072
	s_add_u32 s46, s46, 0x2000
	s_addc_u32 s47, s47, 0
	s_mov_b32 m0, s52
	v_lshl_add_u64 v[230:231], s[46:47], 0, v[128:129]
	ds_read_b128 v[184:187], v153 offset:32768
	ds_read_b128 v[188:191], v153 offset:33792
	ds_read_b128 v[192:195], v153 offset:34816
	ds_read_b128 v[196:199], v153 offset:35840
	ds_read_b128 v[202:205], v153 offset:36864
	ds_read_b128 v[206:209], v153 offset:37888
	ds_read_b128 v[210:213], v153 offset:38912
	ds_read_b128 v[214:217], v153 offset:39936
	global_load_lds_dwordx4 v[230:231], off
	v_lshl_add_u64 v[230:231], s[46:47], 0, v[132:133]
	s_mov_b32 m0, s53
	s_nop 0
	global_load_lds_dwordx4 v[230:231], off
	s_waitcnt vmcnt(8)
	s_waitcnt lgkmcnt(0)
	s_barrier
	s_setprio 1
	s_waitcnt lgkmcnt(0)
	v_mfma_f32_16x16x32_bf16 v[124:127], v[144:147], v[184:187], v[124:127]
	v_mfma_f32_16x16x32_bf16 v[120:123], v[160:163], v[184:187], v[120:123]
	v_mfma_f32_16x16x32_bf16 v[108:111], v[144:147], v[192:195], v[108:111]
	v_mfma_f32_16x16x32_bf16 v[104:107], v[160:163], v[192:195], v[104:107]
	v_mfma_f32_16x16x32_bf16 v[92:95], v[144:147], v[202:205], v[92:95]
	v_mfma_f32_16x16x32_bf16 v[88:91], v[160:163], v[202:205], v[88:91]
	v_mfma_f32_16x16x32_bf16 v[76:79], v[144:147], v[210:213], v[76:79]
	v_mfma_f32_16x16x32_bf16 v[72:75], v[160:163], v[210:213], v[72:75]
	v_mfma_f32_16x16x32_bf16 v[124:127], v[156:159], v[188:191], v[124:127]
	v_mfma_f32_16x16x32_bf16 v[120:123], v[164:167], v[188:191], v[120:123]
	v_mfma_f32_16x16x32_bf16 v[108:111], v[156:159], v[196:199], v[108:111]
	v_mfma_f32_16x16x32_bf16 v[104:107], v[164:167], v[196:199], v[104:107]
	v_mfma_f32_16x16x32_bf16 v[92:95], v[156:159], v[206:209], v[92:95]
	v_mfma_f32_16x16x32_bf16 v[88:91], v[164:167], v[206:209], v[88:91]
	v_mfma_f32_16x16x32_bf16 v[76:79], v[156:159], v[214:217], v[76:79]
	v_mfma_f32_16x16x32_bf16 v[72:75], v[164:167], v[214:217], v[72:75]
	s_setprio 0
	s_setprio 1
	v_mfma_f32_16x16x32_bf16 v[116:119], v[168:171], v[184:187], v[116:119]
	v_mfma_f32_16x16x32_bf16 v[112:115], v[176:179], v[184:187], v[112:115]
	v_mfma_f32_16x16x32_bf16 v[100:103], v[168:171], v[192:195], v[100:103]
	v_mfma_f32_16x16x32_bf16 v[96:99], v[176:179], v[192:195], v[96:99]
	v_mfma_f32_16x16x32_bf16 v[84:87], v[168:171], v[202:205], v[84:87]
	v_mfma_f32_16x16x32_bf16 v[80:83], v[176:179], v[202:205], v[80:83]
	v_mfma_f32_16x16x32_bf16 v[68:71], v[168:171], v[210:213], v[68:71]
	v_mfma_f32_16x16x32_bf16 v[64:67], v[176:179], v[210:213], v[64:67]
	v_mfma_f32_16x16x32_bf16 v[116:119], v[172:175], v[188:191], v[116:119]
	v_mfma_f32_16x16x32_bf16 v[112:115], v[180:183], v[188:191], v[112:115]
	v_mfma_f32_16x16x32_bf16 v[100:103], v[172:175], v[196:199], v[100:103]
	v_mfma_f32_16x16x32_bf16 v[96:99], v[180:183], v[196:199], v[96:99]
	v_mfma_f32_16x16x32_bf16 v[84:87], v[172:175], v[206:209], v[84:87]
	v_mfma_f32_16x16x32_bf16 v[80:83], v[180:183], v[206:209], v[80:83]
	v_mfma_f32_16x16x32_bf16 v[68:71], v[172:175], v[214:217], v[68:71]
	v_mfma_f32_16x16x32_bf16 v[64:67], v[180:183], v[214:217], v[64:67]
	s_setprio 0
	s_barrier
; #define PG8_STAGE(bufoff, gbase, voff) do { _Pragma("unroll") for (int _i = 0; _i < 2; ++_i) \
;         __builtin_amdgcn_global_load_lds((const unsigned*)((const char*)(gbase) + (voff)[_i]), (PG8_LAS unsigned*)(lds + (bufoff) + ldsw + _i * 8192), 16, 0, 0); } while (0)
; #define PG8_LDA(dst, b, h) do { _Pragma("unroll") for (int m = 0; m < 4; ++m) _Pragma("unroll") for (int k = 0; k < 2; ++k) dst[m][k] = *(const PG8_LAS bf16x8*)(lds + PG8_SA(b, h) + aoff + m * 2048 + k * 1024); } while (0)
; #define PG8_MMA(ai, bj, At, Bt) do { __builtin_amdgcn_s_setprio(1); _Pragma("unroll") for (int m = 0; m < 4; ++m) _Pragma("unroll") for (int n = 0; n < 2; ++n) _Pragma("unroll") for (int k = 0; k < 2; ++k) \
;         acc[ai][bj][m][n] = __builtin_amdgcn_mfma_f32_16x16x32_bf16(Bt[n][k], At[m][k], acc[ai][bj][m][n], 0, 0, 0); __builtin_amdgcn_s_setprio(0); } while (0)
; #define PG8_WAIT_V(n) asm volatile("s_waitcnt vmcnt(" #n ")" ::: "memory")
; #define PG8_WAIT_L(n) asm volatile("s_waitcnt lgkmcnt(" #n ")" ::: "memory")
; #define PG8_BAR __builtin_amdgcn_s_barrier()
; #define PG8_SCHED __builtin_amdgcn_sched_barrier(0)
; template <class Epi, class Sched, bool ALIGN_EPI = false, bool SP2 = false>
; __device__ __forceinline__ void gemm_phase(PG8_LAS unsigned char* lds, const Gemm g, const Sched& S, const Epi& E) {
;     ...
;             PG8_LDA(At, 1, 1); PG8_STAGE(PG8_SB(1, 0), b3, voffB); PG8_STAGE(PG8_SB(1, 1), b3 + hstep, voffB); PG8_STAGE(PG8_SA(1, 0), a3, voffA);
;             PG8_WAIT_V(8); PG8_WAIT_L(0); PG8_BAR; PG8_MMA(1, 0, At, B0); PG8_MMA(1, 1, At, B1); PG8_BAR; PG8_SCHED;
	s_add_i32 s16, s16, s49
	v_lshl_add_u64 v[218:219], v[218:219], 0, s[36:37]
	s_mov_b32 m0, s16
	ds_read_b128 v[184:187], v153 offset:49152
	ds_read_b128 v[188:191], v153 offset:50176
	ds_read_b128 v[192:195], v153 offset:51200
	ds_read_b128 v[196:199], v153 offset:52224
	ds_read_b128 v[202:205], v153 offset:53248
	ds_read_b128 v[206:209], v153 offset:54272
	ds_read_b128 v[210:213], v153 offset:55296
	ds_read_b128 v[214:217], v153 offset:56320
	global_load_lds_dwordx4 v[218:219], off
	v_lshl_add_u64 v[218:219], v[220:221], 0, s[36:37]
	s_add_i32 m0, s16, 0x2000
	s_add_i32 s16, s17, s49
	global_load_lds_dwordx4 v[218:219], off
	v_lshl_add_u64 v[218:219], v[222:223], 0, s[36:37]
	s_mov_b32 m0, s16
	s_nop 0
	global_load_lds_dwordx4 v[218:219], off
	v_lshl_add_u64 v[218:219], v[224:225], 0, s[36:37]
	s_add_i32 m0, s16, 0x2000
	s_nop 0
	global_load_lds_dwordx4 v[218:219], off
	v_lshl_add_u64 v[218:219], v[226:227], 0, s[100:101]
	s_mov_b32 m0, s54
	s_nop 0
	global_load_lds_dwordx4 v[218:219], off
	v_lshl_add_u64 v[218:219], v[228:229], 0, s[100:101]
	s_mov_b32 m0, s55
	s_nop 0
	global_load_lds_dwordx4 v[218:219], off
	s_waitcnt vmcnt(8)
	s_waitcnt lgkmcnt(0)
	s_barrier
	s_setprio 1
	s_waitcnt lgkmcnt(0)
	v_mfma_f32_16x16x32_bf16 v[60:63], v[144:147], v[184:187], v[60:63]
	v_mfma_f32_16x16x32_bf16 v[56:59], v[160:163], v[184:187], v[56:59]
	v_mfma_f32_16x16x32_bf16 v[44:47], v[144:147], v[192:195], v[44:47]
	v_mfma_f32_16x16x32_bf16 v[40:43], v[160:163], v[192:195], v[40:43]
	v_mfma_f32_16x16x32_bf16 v[28:31], v[144:147], v[202:205], v[28:31]
	v_mfma_f32_16x16x32_bf16 v[24:27], v[160:163], v[202:205], v[24:27]
	v_mfma_f32_16x16x32_bf16 v[12:15], v[144:147], v[210:213], v[12:15]
	v_mfma_f32_16x16x32_bf16 v[8:11], v[160:163], v[210:213], v[8:11]
	v_mfma_f32_16x16x32_bf16 v[60:63], v[156:159], v[188:191], v[60:63]
	v_mfma_f32_16x16x32_bf16 v[56:59], v[164:167], v[188:191], v[56:59]
	v_mfma_f32_16x16x32_bf16 v[44:47], v[156:159], v[196:199], v[44:47]
	v_mfma_f32_16x16x32_bf16 v[40:43], v[164:167], v[196:199], v[40:43]
	v_mfma_f32_16x16x32_bf16 v[28:31], v[156:159], v[206:209], v[28:31]
	v_mfma_f32_16x16x32_bf16 v[24:27], v[164:167], v[206:209], v[24:27]
	v_mfma_f32_16x16x32_bf16 v[12:15], v[156:159], v[214:217], v[12:15]
	v_mfma_f32_16x16x32_bf16 v[8:11], v[164:167], v[214:217], v[8:11]
	s_setprio 0
	s_setprio 1
	v_mfma_f32_16x16x32_bf16 v[52:55], v[168:171], v[184:187], v[52:55]
	v_mfma_f32_16x16x32_bf16 v[48:51], v[176:179], v[184:187], v[48:51]
	v_mfma_f32_16x16x32_bf16 v[36:39], v[168:171], v[192:195], v[36:39]
	v_mfma_f32_16x16x32_bf16 v[32:35], v[176:179], v[192:195], v[32:35]
	v_mfma_f32_16x16x32_bf16 v[20:23], v[168:171], v[202:205], v[20:23]
	v_mfma_f32_16x16x32_bf16 v[16:19], v[176:179], v[202:205], v[16:19]
	v_mfma_f32_16x16x32_bf16 v[4:7], v[168:171], v[210:213], v[4:7]
	v_mfma_f32_16x16x32_bf16 v[0:3], v[176:179], v[210:213], v[0:3]
	v_mfma_f32_16x16x32_bf16 v[52:55], v[172:175], v[188:191], v[52:55]
	v_mfma_f32_16x16x32_bf16 v[48:51], v[180:183], v[188:191], v[48:51]
	v_mfma_f32_16x16x32_bf16 v[36:39], v[172:175], v[196:199], v[36:39]
	v_mfma_f32_16x16x32_bf16 v[32:35], v[180:183], v[196:199], v[32:35]
	v_mfma_f32_16x16x32_bf16 v[20:23], v[172:175], v[206:209], v[20:23]
	v_mfma_f32_16x16x32_bf16 v[16:19], v[180:183], v[206:209], v[16:19]
	v_mfma_f32_16x16x32_bf16 v[4:7], v[172:175], v[214:217], v[4:7]
	v_mfma_f32_16x16x32_bf16 v[0:3], v[180:183], v[214:217], v[0:3]
	s_setprio 0
	s_barrier
	s_add_u32 s44, s44, 0x10000
	s_addc_u32 s45, s45, 0
	s_add_u32 s68, s68, 0x100
	s_addc_u32 s69, s69, 0
	s_cmp_ge_i32 s70, s57
	s_mov_b32 s46, s70
	s_cbranch_scc0 .LBB0_1104
